# attention rewritten: K/V tiles staged once per WG in LDS via LDS-DMA ring (shared by 8 head waves); W_out epilogue rstd loads de-serialised
# speedup vs baseline: 1.0392x; 1.0392x over previous
; #define INP(k) inptr(k)
; #define WSPTR() kptr(224)
; __device__ __forceinline__ void attn_phase(const Args& a, LAS unsigned char* lds, int layer, int G, int vb) {
;     ...
;     const bf16* proj = (const bf16*)(WSPTR() + WS_PROJ); const bf16* vT = (const bf16*)(WSPTR() + WS_VT); bf16* an = (bf16*)(WSPTR() + WS_MIX); const float* ssq2p = (const float*)(WSPTR() + WS_SSQ2);
;     const float sinkv = INP(8)[layer * 8 + h] * LOG2E;
;     const int ql = lane & 31, hi = lane >> 5;
;     int par = 0;
;     for (int ui = vb; ui < 1024; ui += G, par ^= 1) {
;         const int b = ui & 7, q0 = (ui >> 3) * 32, rowq = b * SEQ + q0;
;         const bf16* qp = proj + (size_t)(rowq + ql) * DIN + h * 64 + 8 * hi;
;         bf16x8 qf[4];
; #pragma unroll
;         for (int kk = 0; kk < 4; ++kk) qf[kk] = *(const bf16x8*)(qp + 16 * kk);
;         float m = sinkv, lsum = 1.0f;
;         f32x16 o0, o1;
; #pragma unroll
;         for (int r = 0; r < 16; ++r) { o0[r] = 0.f; o1[r] = 0.f; }
;         const bf16* vbase = vT + ((size_t)(b * 2 + kvh) * 64 + ql) * SEQ + 4 * hi;
;         const bf16* kbase = proj + (size_t)(b * SEQ + ql) * DIN + 512 + kvh * 64 + 8 * hi;
;         const int rb = ui >> 3, kt_lo = (4 - rb) > 0 ? (4 - rb) : 0, kt_hi = (132 - rb) < 9 ? (132 - rb) : 9;
;         bf16x8 kf[4]; s16x4 vf[2][2][2];
.LBB0_671:
	s_or_b64 exec, exec, s[4:5]
	v_readlane_b32 s22, v254, 5
	v_readlane_b32 s23, v254, 6
	s_movk_i32 s8, 0xe0
	s_waitcnt lgkmcnt(0)
	s_movk_i32 s7, 0xe0
	s_movk_i32 s6, 0xe0
	s_movk_i32 s5, 0xe0
	s_mov_b32 s4, 64
	s_andn2_b64 vcc, exec, s[22:23]
	s_barrier
	s_cmpk_gt_i32 s33, 0x3ff
	s_cbranch_scc1 .LBB0_686
	s_load_dwordx2 s[4:5], s[0:1], 0xe0
	s_load_dwordx2 s[76:77], s[0:1], 0x40
	v_readfirstlane_b32 s18, v209
	v_and_b32_e32 v160, 63, v209
	s_lshr_b32 s18, s18, 6
	v_and_b32_e32 v2, 31, v160
	v_lshrrev_b32_e32 v3, 5, v160
	s_lshr_b32 s19, s18, 2
	s_and_b32 s22, s18, 3
	s_lshl_b32 s78, s17, 3
	s_add_i32 s78, s78, s18
	s_lshl_b32 s78, s78, 2
	s_waitcnt lgkmcnt(0)
	s_load_dword s45, s[76:77], s78
	v_lshrrev_b32_e32 v161, 3, v160
	v_and_b32_e32 v178, 7, v160
	v_xor_b32_e32 v178, v178, v161
	v_mul_u32_u24_e32 v5, 0xa00, v161
	v_lshl_add_u32 v5, v178, 4, v5
	v_lshrrev_b32_e32 v161, 2, v160
	v_lshlrev_b32_e32 v6, 13, v161
	v_bfe_u32 v178, v160, 4, 2
	v_and_b32_e32 v179, 3, v160
	v_xor_b32_e32 v178, v178, v179
	v_lshl_add_u32 v6, v178, 4, v6
	s_mul_i32 s78, s18, 0x500
	s_add_i32 s78, s78, 0x80
	v_lshlrev_b32_e32 v161, 4, v3
	v_lshlrev_b32_e32 v178, 2, v2
	v_sub_u32_e32 v7, v161, v178
	v_add_u32_e32 v7, s78, v7
	v_and_b32_e32 v161, 7, v2
	v_lshlrev_b32_e32 v178, 7, v2
	v_or_b32_e32 v179, 0, v3
	v_xor_b32_e32 v179, v179, v161
	v_lshl_add_u32 v142, v179, 4, v178
	v_or_b32_e32 v179, 2, v3
	v_xor_b32_e32 v179, v179, v161
	v_lshl_add_u32 v143, v179, 4, v178
	v_or_b32_e32 v179, 4, v3
	v_xor_b32_e32 v179, v179, v161
	v_lshl_add_u32 v144, v179, 4, v178
	v_or_b32_e32 v179, 6, v3
	v_xor_b32_e32 v179, v179, v161
	v_lshl_add_u32 v145, v179, 4, v178
	v_bfe_u32 v161, v2, 2, 2
	v_lshlrev_b32_e32 v178, 6, v2
	v_lshl_add_u32 v178, v3, 3, v178
	v_add_u32_e32 v178, 0x1000, v178
	v_xor_b32_e32 v179, 0, v161
	v_lshl_add_u32 v146, v179, 4, v178
	v_xor_b32_e32 v179, 1, v161
	v_lshl_add_u32 v147, v179, 4, v178
	v_xor_b32_e32 v179, 2, v161
	v_lshl_add_u32 v148, v179, 4, v178
	v_xor_b32_e32 v179, 3, v161
	v_lshl_add_u32 v149, v179, 4, v178
	v_mul_u32_u24_e32 v180, 0xa00, v2
	v_lshl_add_u32 v180, v3, 4, v180
	v_lshlrev_b32_e32 v181, 19, v3
	v_lshl_add_u32 v181, v2, 4, v181
	v_lshlrev_b32_e32 v182, 11, v2
	v_lshl_add_u32 v182, v3, 3, v182
	s_lshl_b32 s78, s18, 7
	s_add_i32 s78, s78, 10240
	v_lshl_add_u32 v196, v2, 2, s78
	v_lshlrev_b32_e32 v197, 2, v2
	v_add_u32_e32 v197, 10240, v197
	s_waitcnt lgkmcnt(0)
	v_mov_b32_e32 v183, 0x3fb8aa3b
	v_mul_f32_e32 v183, s45, v183
	s_mov_b32 s23, s33
	s_mov_b32 s37, 0
	s_lshl_b32 s94, s19, 13
	s_lshl_b32 s95, s22, 10
	s_add_i32 s93, s94, 16384
	s_add_i32 s92, s93, s95
.Latt_unit:
	s_and_b32 s52, s23, 7
	s_lshr_b32 s54, s23, 3
	s_sub_i32 s78, 4, s54
	s_max_i32 s78, s78, 0
	s_sub_i32 s79, 0x84, s54
	s_min_i32 s79, s79, 9
	s_sub_i32 s26, s79, s78
	s_lshl_b32 s55, s52, 12
	s_lshl_b32 s81, s54, 5
	s_add_i32 s55, s55, s81
	s_lshl_b32 s83, s78, 5
	s_add_i32 s83, s83, s81
	s_add_i32 s83, s83, 0xffffff80
	s_lshl_b32 s36, s78, 7
	s_lshl_b32 s85, s52, 12
	s_add_i32 s85, s85, s83
	s_lshl_b32 s87, s22, 3
	s_add_i32 s85, s85, s87
	s_mul_i32 s85, s85, 0xa00
	s_lshl_b32 s87, s19, 7
	s_add_i32 s85, s85, s87
	s_add_i32 s85, s85, 0x400
	s_add_u32 s6, s4, s85
	s_addc_u32 s7, s5, 0
	s_add_u32 s6, s6, 0xd800000
	s_addc_u32 s7, s7, 0
	s_lshl_b32 s85, s52, 1
	s_add_i32 s85, s85, s19
	s_lshl_b32 s85, s85, 6
	s_lshl_b32 s87, s22, 4
	s_add_i32 s85, s85, s87
	s_lshl_b32 s85, s85, 13
	s_lshl_b32 s87, s83, 1
	s_add_i32 s85, s85, s87
	s_add_u32 s8, s4, s85
	s_addc_u32 s9, s5, 0
	s_add_u32 s8, s8, 0x18800000
	s_addc_u32 s9, s9, 0
	s_mul_i32 s85, s55, 0xa00
	s_lshl_b32 s87, s18, 7
	s_add_i32 s85, s85, s87
	s_add_u32 s60, s4, s85
	s_addc_u32 s61, s5, 0
	s_add_u32 s60, s60, 0xd800000
	s_addc_u32 s61, s61, 0
	s_lshl_b32 s85, s55, 4
	s_add_u32 s88, s4, s85
	s_addc_u32 s89, s5, 0
	s_add_u32 s88, s88, 0x1d400000
	s_addc_u32 s89, s89, 0
	s_lshl_b32 s85, s55, 11
	s_add_i32 s85, s85, s87
	s_add_u32 s90, s4, s85
	s_addc_u32 s91, s5, 0
	s_add_u32 s90, s90, 0x12800000
	s_addc_u32 s91, s91, 0
	global_load_dwordx4 v[8:11], v180, s[60:61] offset:0
	global_load_dwordx4 v[12:15], v180, s[60:61] offset:32
	global_load_dwordx4 v[16:19], v180, s[60:61] offset:64
	global_load_dwordx4 v[20:23], v180, s[60:61] offset:96
	global_load_dwordx4 v[210:213], v181, s[88:89]
	s_mov_b32 s28, 0
	s_add_i32 m0, s92, 0
	s_nop 0
	global_load_lds_dwordx4 v5, s[6:7]
	s_add_i32 m0, s92, 4096
	s_add_u32 s6, s6, 0x14000
	s_addc_u32 s7, s7, 0
	global_load_lds_dwordx4 v6, s[8:9]
	s_add_u32 s8, s8, 64
	s_addc_u32 s9, s9, 0
	s_add_i32 m0, s92, 16384
	s_nop 0
	global_load_lds_dwordx4 v5, s[6:7]
	s_add_i32 m0, s92, 20480
	s_add_u32 s6, s6, 0x14000
	s_addc_u32 s7, s7, 0
	global_load_lds_dwordx4 v6, s[8:9]
	s_add_u32 s8, s8, 64
	s_addc_u32 s9, s9, 0
	v_mov_b32_e32 v140, v183
	v_mov_b32_e32 v141, 1.0
	v_mov_b32_e32 v24, 0
	v_mov_b32_e32 v25, 0
	v_mov_b32_e32 v26, 0
	v_mov_b32_e32 v27, 0
	v_mov_b32_e32 v28, 0
	v_mov_b32_e32 v29, 0
	v_mov_b32_e32 v30, 0
	v_mov_b32_e32 v31, 0
	v_mov_b32_e32 v32, 0
	v_mov_b32_e32 v33, 0
	v_mov_b32_e32 v34, 0
	v_mov_b32_e32 v35, 0
	v_mov_b32_e32 v36, 0
	v_mov_b32_e32 v37, 0
	v_mov_b32_e32 v38, 0
	v_mov_b32_e32 v39, 0
	v_mov_b32_e32 v46, 0
	v_mov_b32_e32 v47, 0
	v_mov_b32_e32 v48, 0
	v_mov_b32_e32 v49, 0
	v_mov_b32_e32 v50, 0
	v_mov_b32_e32 v51, 0
	v_mov_b32_e32 v52, 0
	v_mov_b32_e32 v53, 0
	v_mov_b32_e32 v54, 0
	v_mov_b32_e32 v55, 0
	v_mov_b32_e32 v56, 0
	v_mov_b32_e32 v57, 0
	v_mov_b32_e32 v58, 0
	v_mov_b32_e32 v59, 0
	v_mov_b32_e32 v60, 0
	v_mov_b32_e32 v61, 0
; __device__ __forceinline__ void attn_phase(const Args& a, LAS unsigned char* lds, int layer, int G, int vb) {
;     ...
;         ATT_LOAD(kf, vf, kt_lo);
;         for (int kt = kt_lo; kt < kt_hi; kt += 2) {
;             { const int ktn = (kt + 1 < kt_hi) ? kt + 1 : kt; ATT_LOAD(kg, vg, ktn); }
;             ATT_TILE(kf, vf, kt);
;             if (kt + 1 < kt_hi) {
;                 { const int ktn = (kt + 2 < kt_hi) ? kt + 2 : kt + 1; ATT_LOAD(kf, vf, ktn); }
;                 ATT_TILE(kg, vg, kt + 1);
;             }
.Latt_tile:
	s_add_i32 s29, s28, 2
	s_and_b32 s29, s29, 3
	s_lshl_b32 s29, s29, 14
	s_add_i32 s29, s29, s92
	s_mov_b32 m0, s29
	s_and_b32 s32, s28, 3
	global_load_lds_dwordx4 v5, s[6:7]
	s_add_i32 m0, s29, 0x1000
	s_add_u32 s6, s6, 0x14000
	s_addc_u32 s7, s7, 0
	global_load_lds_dwordx4 v6, s[8:9]
	s_add_u32 s8, s8, 64
	s_addc_u32 s9, s9, 0
	s_lshl_b32 s32, s32, 14
	s_add_i32 s32, s32, s93
	v_add_u32_e32 v150, s32, v142
	v_add_u32_e32 v151, s32, v143
	v_add_u32_e32 v152, s32, v144
	v_add_u32_e32 v153, s32, v145
	v_add_u32_e32 v154, s32, v146
	v_add_u32_e32 v155, s32, v147
	v_add_u32_e32 v156, s32, v148
	v_add_u32_e32 v158, s32, v149
	v_add_u32_e32 v159, s36, v7
	s_waitcnt vmcnt(4)
	s_barrier
	ds_read2_b32 v[64:65], v159 offset0:0 offset1:1
	ds_read2_b32 v[66:67], v159 offset0:2 offset1:3
	ds_read2_b32 v[68:69], v159 offset0:8 offset1:9
	ds_read2_b32 v[70:71], v159 offset0:10 offset1:11
	ds_read2_b32 v[72:73], v159 offset0:16 offset1:17
	ds_read2_b32 v[74:75], v159 offset0:18 offset1:19
	ds_read2_b32 v[76:77], v159 offset0:24 offset1:25
	ds_read2_b32 v[78:79], v159 offset0:26 offset1:27
	ds_read_b128 v[80:83], v150
	ds_read_b128 v[84:87], v151
	ds_read_b128 v[88:91], v152
	ds_read_b128 v[92:95], v153
	s_add_i32 s36, s36, 0x80
	s_waitcnt lgkmcnt(0)
	v_mfma_f32_32x32x16_bf16 v[64:79], v[80:83], v[8:11], v[64:79]
	v_mfma_f32_32x32x16_bf16 v[64:79], v[84:87], v[12:15], v[64:79]
	v_mfma_f32_32x32x16_bf16 v[64:79], v[88:91], v[16:19], v[64:79]
	v_mfma_f32_32x32x16_bf16 v[64:79], v[92:95], v[20:23], v[64:79]
	ds_read_b64 v[112:113], v154
	ds_read_b64 v[114:115], v155
	ds_read_b64 v[116:117], v156
	ds_read_b64 v[118:119], v158
	ds_read_b64 v[120:121], v154 offset:2048
	ds_read_b64 v[122:123], v155 offset:2048
	ds_read_b64 v[124:125], v156 offset:2048
	ds_read_b64 v[126:127], v158 offset:2048
	s_nop 3
	v_max3_f32 v184, v64, v65, v66
	v_max3_f32 v184, v184, v67, v68
	v_max3_f32 v184, v184, v69, v70
	v_max3_f32 v184, v184, v71, v72
	v_max3_f32 v184, v184, v73, v74
	v_max3_f32 v184, v184, v75, v76
	v_max3_f32 v184, v184, v77, v78
	v_max_f32_e32 v184, v184, v79
	v_mov_b32_e32 v185, v184
	s_nop 1
	v_permlane32_swap_b32_e32 v184, v185
	v_max_f32_e32 v184, v184, v185
	v_cmp_gt_f32_e32 vcc, v184, v140
	s_cbranch_vccz .Latt_norescale
	v_max_f32_e32 v185, v140, v184
	v_sub_f32_e32 v186, v140, v185
	v_exp_f32_e32 v186, v186
	v_mov_b32_e32 v140, v185
	v_mov_b32_e32 v187, v1
	v_mul_f32_e32 v141, v141, v186
	v_pk_mul_f32 v[24:25], v[24:25], v[186:187] op_sel_hi:[1,0]
	v_pk_mul_f32 v[26:27], v[26:27], v[186:187] op_sel_hi:[1,0]
	v_pk_mul_f32 v[28:29], v[28:29], v[186:187] op_sel_hi:[1,0]
	v_pk_mul_f32 v[30:31], v[30:31], v[186:187] op_sel_hi:[1,0]
	v_pk_mul_f32 v[32:33], v[32:33], v[186:187] op_sel_hi:[1,0]
	v_pk_mul_f32 v[34:35], v[34:35], v[186:187] op_sel_hi:[1,0]
	v_pk_mul_f32 v[36:37], v[36:37], v[186:187] op_sel_hi:[1,0]
	v_pk_mul_f32 v[38:39], v[38:39], v[186:187] op_sel_hi:[1,0]
	v_pk_mul_f32 v[46:47], v[46:47], v[186:187] op_sel_hi:[1,0]
	v_pk_mul_f32 v[48:49], v[48:49], v[186:187] op_sel_hi:[1,0]
	v_pk_mul_f32 v[50:51], v[50:51], v[186:187] op_sel_hi:[1,0]
	v_pk_mul_f32 v[52:53], v[52:53], v[186:187] op_sel_hi:[1,0]
	v_pk_mul_f32 v[54:55], v[54:55], v[186:187] op_sel_hi:[1,0]
	v_pk_mul_f32 v[56:57], v[56:57], v[186:187] op_sel_hi:[1,0]
	v_pk_mul_f32 v[58:59], v[58:59], v[186:187] op_sel_hi:[1,0]
	v_pk_mul_f32 v[60:61], v[60:61], v[186:187] op_sel_hi:[1,0]
.Latt_norescale:
	v_sub_f32_e32 v64, v64, v140
	v_sub_f32_e32 v65, v65, v140
	v_sub_f32_e32 v66, v66, v140
	v_sub_f32_e32 v67, v67, v140
	v_sub_f32_e32 v68, v68, v140
	v_sub_f32_e32 v69, v69, v140
	v_sub_f32_e32 v70, v70, v140
	v_sub_f32_e32 v71, v71, v140
	v_sub_f32_e32 v72, v72, v140
	v_sub_f32_e32 v73, v73, v140
	v_sub_f32_e32 v74, v74, v140
	v_sub_f32_e32 v75, v75, v140
	v_sub_f32_e32 v76, v76, v140
	v_sub_f32_e32 v77, v77, v140
	v_sub_f32_e32 v78, v78, v140
	v_sub_f32_e32 v79, v79, v140
	v_exp_f32_e32 v64, v64
	v_exp_f32_e32 v65, v65
	v_exp_f32_e32 v66, v66
	v_exp_f32_e32 v67, v67
	v_exp_f32_e32 v68, v68
	v_exp_f32_e32 v69, v69
	v_exp_f32_e32 v70, v70
	v_exp_f32_e32 v71, v71
	v_exp_f32_e32 v72, v72
	v_exp_f32_e32 v73, v73
	v_exp_f32_e32 v74, v74
	v_exp_f32_e32 v75, v75
	v_exp_f32_e32 v76, v76
	v_exp_f32_e32 v77, v77
	v_exp_f32_e32 v78, v78
	v_exp_f32_e32 v79, v79
	v_add_f32_e32 v188, v64, v65
	v_add_f32_e32 v189, v66, v67
	v_add_f32_e32 v190, v68, v69
	v_add_f32_e32 v191, v70, v71
	v_add_f32_e32 v192, v72, v73
	v_add_f32_e32 v193, v74, v75
	v_add_f32_e32 v194, v76, v77
	v_add_f32_e32 v195, v78, v79
	v_add_f32_e32 v188, v188, v189
	v_add_f32_e32 v189, v190, v191
	v_add_f32_e32 v190, v192, v193
	v_add_f32_e32 v191, v194, v195
	v_add_f32_e32 v188, v188, v189
	v_add_f32_e32 v190, v190, v191
	v_add_f32_e32 v188, v188, v190
	v_mov_b32_e32 v189, v188
	v_cvt_pk_bf16_f32 v128, v64, v65
	v_cvt_pk_bf16_f32 v129, v66, v67
	v_cvt_pk_bf16_f32 v130, v68, v69
	v_cvt_pk_bf16_f32 v131, v70, v71
	v_permlane32_swap_b32_e32 v188, v189
	v_cvt_pk_bf16_f32 v136, v72, v73
	v_cvt_pk_bf16_f32 v137, v74, v75
	v_cvt_pk_bf16_f32 v138, v76, v77
	v_cvt_pk_bf16_f32 v139, v78, v79
	v_add_f32_e32 v188, v188, v189
	v_add_f32_e32 v141, v141, v188
	s_waitcnt lgkmcnt(0)
	v_mfma_f32_32x32x16_bf16 v[24:39], v[112:115], v[128:131], v[24:39]
	v_mfma_f32_32x32x16_bf16 v[46:61], v[120:123], v[128:131], v[46:61]
	v_mfma_f32_32x32x16_bf16 v[24:39], v[116:119], v[136:139], v[24:39]
	v_mfma_f32_32x32x16_bf16 v[46:61], v[124:127], v[136:139], v[46:61]
	s_add_i32 s28, s28, 1
	s_cmp_lt_i32 s28, s26
	s_cbranch_scc1 .Latt_tile
; #define LAS __attribute__((address_space(3)))
; __device__ __forceinline__ unsigned pk2(float lo, float hi) { const f32x2 v = {lo, hi}; return __builtin_bit_cast(unsigned, __builtin_convertvector(v, bf16x2_t)); }
; __device__ __forceinline__ void attn_phase(const Args& a, LAS unsigned char* lds, int layer, int G, int vb) {
;     ...
;         const float inv = 1.0f / lsum;
;         float ss = 0.f;
; #pragma unroll
;         for (int r = 0; r < 16; ++r) { o0[r] *= inv; o1[r] *= inv; ss += o0[r] * o0[r] + o1[r] * o1[r]; }
;         ss += __shfl_xor(ss, 32);
;         LAS float* rd = red + par * 256;
;         if (hi == 0) rd[h * 32 + ql] = ss;
;         __syncthreads();
;         float tot = 0.f;
; #pragma unroll
;         for (int hh = 0; hh < 8; ++hh) tot += rd[hh * 32 + ql];
;         const f32x4 sq = *(const f32x4*)(ssq2p + ((size_t)hi * NT + rowq + ql) * 4);
;         float ts = (sq[0] + sq[1]) + (sq[2] + sq[3]); ts += __shfl_xor(ts, 32);
;         const float rstd = __builtin_amdgcn_rsqf(tot * (1.0f / 512.0f) + 1e-6f) * __builtin_amdgcn_sqrtf(ts * (1.0f / 512.0f) + 1e-6f);
;         bf16* op = an + (size_t)(rowq + ql) * 1024 + h * 64 + 4 * hi;
; #pragma unroll
;         for (int g4 = 0; g4 < 4; ++g4) {
;             u32x2 w0, w1;
;             w0.x = pk2(o0[4 * g4] * rstd, o0[4 * g4 + 1] * rstd); w0.y = pk2(o0[4 * g4 + 2] * rstd, o0[4 * g4 + 3] * rstd);
;             w1.x = pk2(o1[4 * g4] * rstd, o1[4 * g4 + 1] * rstd); w1.y = pk2(o1[4 * g4 + 2] * rstd, o1[4 * g4 + 3] * rstd);
;             *(u32x2*)(op + 8 * g4) = w0; *(u32x2*)(op + 32 + 8 * g4) = w1;
;         }
	s_nop 11
	v_rcp_f32_e32 v186, v141
	v_mov_b32_e32 v187, v1
	v_fma_f32 v184, -v141, v186, 1.0
	v_fmac_f32_e32 v186, v184, v186
	v_mov_b32_e32 v188, 0
	v_mov_b32_e32 v189, 0
	v_mov_b32_e32 v190, 0
	v_mov_b32_e32 v191, 0
	v_pk_mul_f32 v[24:25], v[24:25], v[186:187] op_sel_hi:[1,0]
	v_pk_mul_f32 v[26:27], v[26:27], v[186:187] op_sel_hi:[1,0]
	v_pk_mul_f32 v[28:29], v[28:29], v[186:187] op_sel_hi:[1,0]
	v_pk_mul_f32 v[30:31], v[30:31], v[186:187] op_sel_hi:[1,0]
	v_pk_mul_f32 v[32:33], v[32:33], v[186:187] op_sel_hi:[1,0]
	v_pk_mul_f32 v[34:35], v[34:35], v[186:187] op_sel_hi:[1,0]
	v_pk_mul_f32 v[36:37], v[36:37], v[186:187] op_sel_hi:[1,0]
	v_pk_mul_f32 v[38:39], v[38:39], v[186:187] op_sel_hi:[1,0]
	v_pk_mul_f32 v[46:47], v[46:47], v[186:187] op_sel_hi:[1,0]
	v_pk_mul_f32 v[48:49], v[48:49], v[186:187] op_sel_hi:[1,0]
	v_pk_mul_f32 v[50:51], v[50:51], v[186:187] op_sel_hi:[1,0]
	v_pk_mul_f32 v[52:53], v[52:53], v[186:187] op_sel_hi:[1,0]
	v_pk_mul_f32 v[54:55], v[54:55], v[186:187] op_sel_hi:[1,0]
	v_pk_mul_f32 v[56:57], v[56:57], v[186:187] op_sel_hi:[1,0]
	v_pk_mul_f32 v[58:59], v[58:59], v[186:187] op_sel_hi:[1,0]
	v_pk_mul_f32 v[60:61], v[60:61], v[186:187] op_sel_hi:[1,0]
	v_fmac_f32_e32 v188, v24, v24
	v_fmac_f32_e32 v189, v25, v25
	v_fmac_f32_e32 v190, v26, v26
	v_fmac_f32_e32 v191, v27, v27
	v_fmac_f32_e32 v188, v28, v28
	v_fmac_f32_e32 v189, v29, v29
	v_fmac_f32_e32 v190, v30, v30
	v_fmac_f32_e32 v191, v31, v31
	v_fmac_f32_e32 v188, v32, v32
	v_fmac_f32_e32 v189, v33, v33
	v_fmac_f32_e32 v190, v34, v34
	v_fmac_f32_e32 v191, v35, v35
	v_fmac_f32_e32 v188, v36, v36
	v_fmac_f32_e32 v189, v37, v37
	v_fmac_f32_e32 v190, v38, v38
	v_fmac_f32_e32 v191, v39, v39
	v_fmac_f32_e32 v188, v46, v46
	v_fmac_f32_e32 v189, v47, v47
	v_fmac_f32_e32 v190, v48, v48
	v_fmac_f32_e32 v191, v49, v49
	v_fmac_f32_e32 v188, v50, v50
	v_fmac_f32_e32 v189, v51, v51
	v_fmac_f32_e32 v190, v52, v52
	v_fmac_f32_e32 v191, v53, v53
	v_fmac_f32_e32 v188, v54, v54
	v_fmac_f32_e32 v189, v55, v55
	v_fmac_f32_e32 v190, v56, v56
	v_fmac_f32_e32 v191, v57, v57
	v_fmac_f32_e32 v188, v58, v58
	v_fmac_f32_e32 v189, v59, v59
	v_fmac_f32_e32 v190, v60, v60
	v_fmac_f32_e32 v191, v61, v61
	v_add_f32_e32 v188, v188, v189
	v_add_f32_e32 v190, v190, v191
	v_add_f32_e32 v188, v188, v190
	v_mov_b32_e32 v189, v188
	v_add_u32_e32 v198, s37, v196
	v_add_u32_e32 v199, s37, v197
	v_permlane32_swap_b32_e32 v188, v189
	v_add_f32_e32 v188, v188, v189
	ds_write_b32 v198, v188
	s_waitcnt vmcnt(0) lgkmcnt(0)
	s_barrier
	ds_read2_b32 v[200:201], v199 offset0:0 offset1:32
	ds_read2_b32 v[202:203], v199 offset0:64 offset1:96
	ds_read2_b32 v[204:205], v199 offset0:128 offset1:160
	ds_read2_b32 v[206:207], v199 offset0:192 offset1:224
	v_add_f32_e32 v192, v210, v211
	v_add_f32_e32 v193, v212, v213
	v_add_f32_e32 v192, v192, v193
	v_mov_b32_e32 v193, v192
	s_nop 1
	v_permlane32_swap_b32_e32 v192, v193
	v_add_f32_e32 v192, v192, v193
	v_fmamk_f32 v192, v192, 0x3b000000, v220
	v_sqrt_f32_e32 v192, v192
	s_waitcnt lgkmcnt(0)
	v_add_f32_e32 v200, v200, v201
	v_add_f32_e32 v202, v202, v203
	v_add_f32_e32 v204, v204, v205
	v_add_f32_e32 v206, v206, v207
	v_add_f32_e32 v200, v200, v202
	v_add_f32_e32 v204, v204, v206
	v_add_f32_e32 v200, v200, v204
	v_fmamk_f32 v200, v200, 0x3b000000, v220
	v_rsq_f32_e32 v200, v200
	v_mov_b32_e32 v201, v1
	v_mul_f32_e32 v200, v200, v192
	v_pk_mul_f32 v[24:25], v[24:25], v[200:201] op_sel_hi:[1,0]
	v_pk_mul_f32 v[26:27], v[26:27], v[200:201] op_sel_hi:[1,0]
	v_cvt_pk_bf16_f32 v214, v24, v25
	v_cvt_pk_bf16_f32 v215, v26, v27
	global_store_dwordx2 v182, v[214:215], s[90:91] offset:0
	s_nop 0
	v_pk_mul_f32 v[28:29], v[28:29], v[200:201] op_sel_hi:[1,0]
	v_pk_mul_f32 v[30:31], v[30:31], v[200:201] op_sel_hi:[1,0]
	v_cvt_pk_bf16_f32 v214, v28, v29
	v_cvt_pk_bf16_f32 v215, v30, v31
	global_store_dwordx2 v182, v[214:215], s[90:91] offset:16
	s_nop 0
	v_pk_mul_f32 v[32:33], v[32:33], v[200:201] op_sel_hi:[1,0]
	v_pk_mul_f32 v[34:35], v[34:35], v[200:201] op_sel_hi:[1,0]
	v_cvt_pk_bf16_f32 v214, v32, v33
	v_cvt_pk_bf16_f32 v215, v34, v35
	global_store_dwordx2 v182, v[214:215], s[90:91] offset:32
	s_nop 0
	v_pk_mul_f32 v[36:37], v[36:37], v[200:201] op_sel_hi:[1,0]
	v_pk_mul_f32 v[38:39], v[38:39], v[200:201] op_sel_hi:[1,0]
	v_cvt_pk_bf16_f32 v214, v36, v37
	v_cvt_pk_bf16_f32 v215, v38, v39
	global_store_dwordx2 v182, v[214:215], s[90:91] offset:48
	s_nop 0
	v_pk_mul_f32 v[46:47], v[46:47], v[200:201] op_sel_hi:[1,0]
	v_pk_mul_f32 v[48:49], v[48:49], v[200:201] op_sel_hi:[1,0]
	v_cvt_pk_bf16_f32 v214, v46, v47
	v_cvt_pk_bf16_f32 v215, v48, v49
	global_store_dwordx2 v182, v[214:215], s[90:91] offset:64
	s_nop 0
	v_pk_mul_f32 v[50:51], v[50:51], v[200:201] op_sel_hi:[1,0]
	v_pk_mul_f32 v[52:53], v[52:53], v[200:201] op_sel_hi:[1,0]
	v_cvt_pk_bf16_f32 v214, v50, v51
	v_cvt_pk_bf16_f32 v215, v52, v53
	global_store_dwordx2 v182, v[214:215], s[90:91] offset:80
	s_nop 0
	v_pk_mul_f32 v[54:55], v[54:55], v[200:201] op_sel_hi:[1,0]
	v_pk_mul_f32 v[56:57], v[56:57], v[200:201] op_sel_hi:[1,0]
	v_cvt_pk_bf16_f32 v214, v54, v55
	v_cvt_pk_bf16_f32 v215, v56, v57
	global_store_dwordx2 v182, v[214:215], s[90:91] offset:96
	s_nop 0
	v_pk_mul_f32 v[58:59], v[58:59], v[200:201] op_sel_hi:[1,0]
	v_pk_mul_f32 v[60:61], v[60:61], v[200:201] op_sel_hi:[1,0]
	v_cvt_pk_bf16_f32 v214, v58, v59
	v_cvt_pk_bf16_f32 v215, v60, v61
	global_store_dwordx2 v182, v[214:215], s[90:91] offset:112
	s_nop 0
	s_xor_b32 s37, s37, 0x400
	s_add_i32 s23, s23, s20
	s_cmpk_lt_i32 s23, 0x400
	s_cbranch_scc1 .Latt_unit

; #define ssq2 ((float*)(WSPTR() + WS_SSQ2))
;     __device__ __forceinline__ void operator()(const f32x4 (&acc)[2][2][4][2], const Unit& u, int wr, int wc, int fr, int fq) const {
;     ...
;         float scv[8];
; #pragma unroll
;         for (int i = 0; i < 8; ++i) scv[i] = ROWSCALE ? row_rstd8(ssq2, row0 + (i >> 2) * HALF + (i & 3) * 16, fq) : scale;
; #pragma unroll
;         for (int ai = 0; ai < 2; ++ai) {
;             u32x4 xv[4][2];
; #pragma unroll
;             for (int m = 0; m < 4; ++m)
; #pragma unroll
;                 for (int bj = 0; bj < 2; ++bj) xv[m][bj] = *(const u32x4*)(xb + (size_t)(row0 + ai * HALF + m * 16) * 1024 + col0 + bj * HALF);
.LBB0_755:
	v_and_b32_e32 v131, 64, v218
	v_xor_b32_e32 v130, 16, v218
	v_add_u32_e32 v131, 64, v131
	v_cmp_lt_i32_e32 vcc, v130, v131
	v_lshl_add_u32 v196, s52, 8, v226
	v_ashrrev_i32_e32 v197, 31, v196
	v_cndmask_b32_e32 v130, v218, v130, vcc
	v_lshlrev_b32_e32 v231, 2, v130
	v_xor_b32_e32 v130, 32, v218
	v_cmp_lt_i32_e32 vcc, v130, v131
	v_or_b32_e32 v204, 16, v196
	v_ashrrev_i32_e32 v205, 31, v204
	v_cndmask_b32_e32 v130, v218, v130, vcc
	v_lshlrev_b32_e32 v230, 2, v130
	v_or_b32_e32 v202, 32, v196
	v_ashrrev_i32_e32 v203, 31, v202
	v_or_b32_e32 v198, 48, v196
	v_ashrrev_i32_e32 v199, 31, v198
	v_add_u32_e32 v194, 0x80, v196
	v_ashrrev_i32_e32 v195, 31, v194
	v_lshl_or_b32 v192, s88, 8, v228
	v_ashrrev_i32_e32 v193, 31, v192
	v_lshlrev_b64 v[214:215], 1, v[192:193]
	v_lshl_add_u64 v[200:201], s[76:77], 0, v[214:215]
	v_lshlrev_b64 v[216:217], 11, v[196:197]
	v_lshlrev_b64 v[212:213], 11, v[204:205]
	v_lshlrev_b64 v[210:211], 11, v[202:203]
	v_lshlrev_b64 v[206:207], 11, v[198:199]
	s_ashr_i32 s89, s88, 31
	s_lshl_b64 s[88:89], s[88:89], 19
	v_lshl_add_u64 v[248:249], v[196:197], 0, v[184:185]
	v_lshl_add_u64 v[248:249], v[248:249], 4, v[186:187]
	global_load_dwordx2 v[246:247], v[248:249], off
	v_lshl_add_u64 v[248:249], v[204:205], 0, v[184:185]
	v_lshl_add_u64 v[248:249], v[248:249], 4, v[186:187]
	global_load_dwordx2 v[244:245], v[248:249], off
	v_lshl_add_u64 v[248:249], v[202:203], 0, v[184:185]
	v_lshl_add_u64 v[248:249], v[248:249], 4, v[186:187]
	global_load_dwordx2 v[242:243], v[248:249], off
	v_lshl_add_u64 v[248:249], v[198:199], 0, v[184:185]
	v_lshl_add_u64 v[248:249], v[248:249], 4, v[186:187]
	global_load_dwordx2 v[240:241], v[248:249], off
	v_lshl_add_u64 v[248:249], v[194:195], 0, v[184:185]
	v_lshl_add_u64 v[248:249], v[248:249], 4, v[186:187]
	global_load_dwordx2 v[238:239], v[248:249], off
	v_add_u32_e32 v250, 0x90, v196
	v_ashrrev_i32_e32 v251, 31, v250
	v_lshl_add_u64 v[248:249], v[250:251], 0, v[184:185]
	v_lshl_add_u64 v[248:249], v[248:249], 4, v[186:187]
	global_load_dwordx2 v[236:237], v[248:249], off
	v_add_u32_e32 v250, 0xa0, v196
	v_ashrrev_i32_e32 v251, 31, v250
	v_lshl_add_u64 v[248:249], v[250:251], 0, v[184:185]
	v_lshl_add_u64 v[248:249], v[248:249], 4, v[186:187]
	global_load_dwordx2 v[234:235], v[248:249], off
	v_add_u32_e32 v250, 0xb0, v196
	v_ashrrev_i32_e32 v251, 31, v250
	v_lshl_add_u64 v[248:249], v[250:251], 0, v[184:185]
	v_lshl_add_u64 v[248:249], v[248:249], 4, v[186:187]
	global_load_dwordx2 v[232:233], v[248:249], off
	v_lshl_add_u64 v[130:131], v[200:201], 0, v[216:217]
	global_load_dwordx4 v[158:161], v[130:131], off
	global_load_dwordx4 v[154:157], v[130:131], off offset:256
	v_lshl_add_u64 v[130:131], v[200:201], 0, v[212:213]
	global_load_dwordx4 v[150:153], v[130:131], off
	global_load_dwordx4 v[146:149], v[130:131], off offset:256
	v_lshl_add_u64 v[130:131], v[200:201], 0, v[210:211]
	global_load_dwordx4 v[142:145], v[130:131], off
	global_load_dwordx4 v[138:141], v[130:131], off offset:256
	v_lshl_add_u64 v[130:131], v[200:201], 0, v[206:207]
	global_load_dwordx4 v[134:137], v[130:131], off
	s_nop 0
	global_load_dwordx4 v[130:133], v[130:131], off offset:256
	s_waitcnt vmcnt(8)
	v_add_f32_e32 v246, v246, v247
	v_add_f32_e32 v244, v244, v245
	v_add_f32_e32 v242, v242, v243
	v_add_f32_e32 v240, v240, v241
	v_add_f32_e32 v238, v238, v239
	v_add_f32_e32 v236, v236, v237
	v_add_f32_e32 v234, v234, v235
	v_add_f32_e32 v232, v232, v233
	ds_bpermute_b32 v247, v231, v246
	ds_bpermute_b32 v245, v231, v244
	ds_bpermute_b32 v243, v231, v242
	ds_bpermute_b32 v241, v231, v240
	ds_bpermute_b32 v239, v231, v238
	ds_bpermute_b32 v237, v231, v236
	ds_bpermute_b32 v235, v231, v234
	ds_bpermute_b32 v233, v231, v232
	s_waitcnt lgkmcnt(0)
; __device__ __forceinline__ unsigned cvt_pk_bf16(float lo, float hi) { const f32x2 v = {lo, hi}; return __builtin_bit_cast(unsigned, __builtin_convertvector(v, bf16x2_t)); }
; __device__ __forceinline__ float bf_lo(unsigned w) { return __uint_as_float(w << 16); }
; __device__ __forceinline__ float bf_hi(unsigned w) { return __uint_as_float(w & 0xffff0000u); }
; #define ssq ((float*)(WSPTR() + WS_SSQ))
;     __device__ __forceinline__ void operator()(const f32x4 (&acc)[2][2][4][2], const Unit& u, int wr, int wc, int fr, int fq) const {
;     ...
;             for (int m = 0; m < 4; ++m) {
;                 const int row = row0 + ai * HALF + m * 16;
;                 const float sc = scv[ai * 4 + m];
;                 float ss = 0.f;
; #pragma unroll
;                 for (int bj = 0; bj < 2; ++bj) {
;                     const u32x4 xw = xv[m][bj]; const f32x4 a0 = acc[ai][bj][m][0] * sc, a1 = acc[ai][bj][m][1] * sc;
;                     float o[8];
;                     o[0] = bf_lo(xw.x) + a0[0]; o[1] = bf_hi(xw.x) + a0[1]; o[2] = bf_lo(xw.y) + a0[2]; o[3] = bf_hi(xw.y) + a0[3];
;                     o[4] = bf_lo(xw.z) + a1[0]; o[5] = bf_hi(xw.z) + a1[1]; o[6] = bf_lo(xw.w) + a1[2]; o[7] = bf_hi(xw.w) + a1[3];
; #pragma unroll
;                     for (int j = 0; j < 8; ++j) ss += o[j] * o[j];
;                     u32x4 w; w.x = cvt_pk_bf16(o[0], o[1]); w.y = cvt_pk_bf16(o[2], o[3]); w.z = cvt_pk_bf16(o[4], o[5]); w.w = cvt_pk_bf16(o[6], o[7]);
;                     *(u32x4*)(xb + (size_t)row * 1024 + col0 + bj * HALF) = w;
;                 }
;                 ss += __shfl_xor(ss, 16); ss += __shfl_xor(ss, 32); if (fq == 0) ssq[((size_t)u.pn * 32768 + row) * 4 + wc] = ss;
	v_add_f32_e32 v246, v246, v247
	v_add_f32_e32 v244, v244, v245
	v_add_f32_e32 v242, v242, v243
	v_add_f32_e32 v240, v240, v241
	v_add_f32_e32 v238, v238, v239
	v_add_f32_e32 v236, v236, v237
	v_add_f32_e32 v234, v234, v235
	v_add_f32_e32 v232, v232, v233
	ds_bpermute_b32 v247, v230, v246
	ds_bpermute_b32 v245, v230, v244
	ds_bpermute_b32 v243, v230, v242
	ds_bpermute_b32 v241, v230, v240
	ds_bpermute_b32 v239, v230, v238
	ds_bpermute_b32 v237, v230, v236
	ds_bpermute_b32 v235, v230, v234
	ds_bpermute_b32 v233, v230, v232
	s_waitcnt lgkmcnt(7)
	v_add_f32_e32 v246, v246, v247
	v_fmamk_f32 v246, v246, 0x3b000000, v220
	v_rsq_f32_e32 v208, v246
	s_waitcnt vmcnt(7)
	v_lshlrev_b32_e32 v246, 16, v158
	v_and_b32_e32 v247, 0xffff0000, v158
	v_lshlrev_b32_e32 v158, 16, v159
	v_and_b32_e32 v159, 0xffff0000, v159
	v_pk_fma_f32 v[128:129], v[128:129], v[208:209], v[158:159] op_sel_hi:[1,0,1]
	v_lshlrev_b32_e32 v158, 16, v160
	v_and_b32_e32 v159, 0xffff0000, v160
	v_pk_fma_f32 v[126:127], v[126:127], v[208:209], v[246:247] op_sel_hi:[1,0,1]
	v_pk_fma_f32 v[158:159], v[122:123], v[208:209], v[158:159] op_sel_hi:[1,0,1]
	v_lshlrev_b32_e32 v122, 16, v161
	v_and_b32_e32 v123, 0xffff0000, v161
	v_pk_fma_f32 v[160:161], v[124:125], v[208:209], v[122:123] op_sel_hi:[1,0,1]
	v_pk_mul_f32 v[246:247], v[126:127], v[126:127]
	v_cvt_pk_bf16_f32 v122, v126, v127
	v_lshl_add_u64 v[126:127], s[76:77], 0, v[216:217]
	v_cvt_pk_bf16_f32 v123, v128, v129
	v_cvt_pk_bf16_f32 v124, v158, v159
	v_cvt_pk_bf16_f32 v125, v160, v161
	v_lshl_add_u64 v[126:127], v[126:127], 0, v[214:215]
	global_store_dwordx4 v[126:127], v[122:125], off
	v_pk_mul_f32 v[248:249], v[128:129], v[128:129]
	v_pk_mul_f32 v[250:251], v[158:159], v[158:159]
	s_waitcnt vmcnt(7)
	v_lshlrev_b32_e32 v122, 16, v154
	v_and_b32_e32 v123, 0xffff0000, v154
	v_pk_fma_f32 v[118:119], v[118:119], v[208:209], v[122:123] op_sel_hi:[1,0,1]
	v_lshlrev_b32_e32 v122, 16, v155
	v_and_b32_e32 v123, 0xffff0000, v155
	v_pk_fma_f32 v[120:121], v[120:121], v[208:209], v[122:123] op_sel_hi:[1,0,1]
	v_lshlrev_b32_e32 v122, 16, v156
	v_and_b32_e32 v123, 0xffff0000, v156
	v_add_f32_e32 v156, v246, v247
	v_add_f32_e32 v156, v248, v156
	v_add_f32_e32 v156, v249, v156
	v_add_f32_e32 v156, v250, v156
	v_pk_mul_f32 v[252:253], v[160:161], v[160:161]
	v_add_f32_e32 v156, v251, v156
	v_pk_fma_f32 v[122:123], v[114:115], v[208:209], v[122:123] op_sel_hi:[1,0,1]
	v_lshlrev_b32_e32 v114, 16, v157
	v_and_b32_e32 v115, 0xffff0000, v157
	v_add_f32_e32 v156, v252, v156
	v_pk_fma_f32 v[124:125], v[116:117], v[208:209], v[114:115] op_sel_hi:[1,0,1]
	v_pk_mul_f32 v[114:115], v[118:119], v[118:119]
	v_add_f32_e32 v156, v253, v156
	v_add_f32_e32 v114, v114, v156
	v_pk_mul_f32 v[116:117], v[120:121], v[120:121]
	v_add_f32_e32 v114, v115, v114
	v_add_f32_e32 v114, v116, v114
	v_pk_mul_f32 v[128:129], v[122:123], v[122:123]
	v_add_f32_e32 v114, v117, v114
	v_add_f32_e32 v114, v128, v114
	v_pk_mul_f32 v[154:155], v[124:125], v[124:125]
	v_add_f32_e32 v114, v129, v114
	v_add_f32_e32 v114, v154, v114
	v_add_f32_e32 v128, v155, v114
	v_cvt_pk_bf16_f32 v114, v118, v119
	v_cvt_pk_bf16_f32 v115, v120, v121
	v_cvt_pk_bf16_f32 v116, v122, v123
	v_cvt_pk_bf16_f32 v117, v124, v125
	global_store_dwordx4 v[126:127], v[114:117], off offset:256
	ds_bpermute_b32 v114, v231, v128
	s_waitcnt lgkmcnt(0)
	v_add_f32_e32 v114, v128, v114
	ds_bpermute_b32 v115, v230, v114
	s_and_saveexec_b64 s[22:23], s[4:5]
	s_cbranch_execz .LBB0_757
	s_add_u32 s26, s54, s88
	s_addc_u32 s27, s55, s89
	v_lshl_add_u64 v[116:117], v[196:197], 4, s[26:27]
	s_lshl_b32 s52, s58, 2
	v_lshl_add_u64 v[116:117], v[116:117], 0, s[52:53]
	s_waitcnt lgkmcnt(0)
	v_add_f32_e32 v114, v114, v115
	global_store_dword v[116:117], v114, off
